# previous version plus FoX leading key-tile skip bound changed from weight<2^-152 to weight<2^-66 of the row max (skipped mass < 2^-53 of the softmax sum, below f64 ulp); outputs not bit-identical to b
# speedup vs baseline: 1.0251x; 1.0118x over previous
; __global__ void __launch_bounds__(MEGA_THREADS, 2) mega(MArgs a) {
;     ...
;                 if (EN_FOX && (sub & SUB_FOX)) {
;                     float gqm = fabsf(in[6][l * 64 + lane]), gkm = fabsf(in[7][l * 64 + lane]);
; #pragma unroll
;                     for (int o = 1; o < 64; o <<= 1) { gqm = fmaxf(gqm, __shfl_xor(gqm, o)); gkm = fmaxf(gkm, __shfl_xor(gkm, o)); }
;                     const float thr = -(152.f + 2.f * C2 * 64.f * gqm * gkm);
.LBB9_233:
	s_and_b64 vcc, exec, s[6:7]
	s_cbranch_vccz .LBB9_349
	s_add_u32 s2, s76, 0x1e100000
	s_addc_u32 s3, s77, 0
	v_writelane_b32 v255, s2, 1
	s_add_u32 s44, s76, 0x1e300000
	s_addc_u32 s45, s77, 0
	v_writelane_b32 v255, s3, 2
	v_readlane_b32 s2, v254, 0
	v_readlane_b32 s3, v254, 1
	s_load_dword s2, s[2:3], 0xe8
	v_writelane_b32 v255, s67, 3
	s_mov_b64 s[6:7], -1
	s_waitcnt lgkmcnt(0)
	s_add_i32 s71, s2, s82
	s_cmp_gt_i32 s67, 1
	s_cbranch_scc0 .LBB9_626
	s_add_u32 s46, s76, 0x1c100000
	s_addc_u32 s47, s77, 0
	s_add_u32 s28, s76, 0x4100000
	s_addc_u32 s29, s77, 0
	s_add_u32 s2, s76, 0x8100000
	s_addc_u32 s3, s77, 0
	s_add_u32 s25, s76, 0x1e200000
	s_addc_u32 s24, s77, 0
	s_add_u32 s60, s76, 0x1e400000
	v_writelane_b32 v255, s2, 4
	s_addc_u32 s61, s77, 0
	s_nop 0
	v_writelane_b32 v255, s3, 5
	s_add_u32 s2, s76, 0x20100000
	s_addc_u32 s3, s77, 0
	v_writelane_b32 v255, s2, 6
	s_nop 1
	v_writelane_b32 v255, s3, 7
	s_add_u32 s2, s76, 0x20200000
	s_addc_u32 s3, s77, 0
	v_writelane_b32 v255, s2, 8
	s_nop 1
	v_writelane_b32 v255, s3, 9
	s_nop 0
	v_readlane_b32 s2, v255, 3
	s_cmp_gt_i32 s2, 2
	v_writelane_b32 v255, s24, 10
	s_cbranch_scc0 .LBB9_454
	s_bitcmp0_b32 s71, 7
	s_cbranch_scc1 .LBB9_350
	s_load_dwordx4 s[4:7], s[84:85], 0x30
	v_readlane_b32 s2, v254, 51
	s_waitcnt vmcnt(0)
	v_xor_b32_e32 v6, 1, v244
	s_add_u32 s79, s76, 0x6100000
	v_lshl_or_b32 v0, s2, 6, v248
	v_lshlrev_b64 v[2:3], 2, v[0:1]
	s_waitcnt lgkmcnt(0)
	v_lshl_add_u64 v[4:5], s[4:5], 0, v[2:3]
	v_lshl_add_u64 v[2:3], s[6:7], 0, v[2:3]
	global_load_dword v2, v[2:3], off
	s_addc_u32 s81, s77, 0
	global_load_dword v0, v[4:5], off
	v_and_b32_e32 v5, 64, v244
	v_add_u32_e32 v5, 64, v5
	v_cmp_lt_i32_e32 vcc, v6, v5
	v_readlane_b32 s3, v254, 52
	s_lshl_b32 s52, s2, 9
	v_cndmask_b32_e32 v6, v244, v6, vcc
	v_lshlrev_b32_e32 v6, 2, v6
	s_lshl_b64 s[2:3], s[52:53], 2
	s_add_u32 s2, s76, s2
	s_addc_u32 s3, s77, s3
	s_add_u32 s18, s2, 0x8000
	s_addc_u32 s19, s3, 0
	v_readlane_b32 s2, v254, 11
	s_add_u32 s2, s2, s82
	s_waitcnt vmcnt(0)
	v_and_b32_e32 v3, 0x7fffffff, v2
	ds_bpermute_b32 v3, v6, v3
	v_and_b32_e32 v4, 0x7fffffff, v0
	ds_bpermute_b32 v4, v6, v4
	v_max_f32_e64 v2, |v2|, |v2|
	v_max_f32_e64 v0, |v0|, |v0|
	s_waitcnt lgkmcnt(1)
	v_max_f32_e32 v3, v3, v3
	v_max_f32_e32 v2, v2, v3
	v_xor_b32_e32 v3, 2, v244
	v_cmp_lt_i32_e32 vcc, v3, v5
	s_waitcnt lgkmcnt(0)
	v_max_f32_e32 v4, v4, v4
	v_max_f32_e32 v0, v0, v4
	v_cndmask_b32_e32 v3, v244, v3, vcc
	v_lshlrev_b32_e32 v3, 2, v3
	ds_bpermute_b32 v4, v3, v0
	ds_bpermute_b32 v3, v3, v2
	v_writelane_b32 v255, s2, 11
	v_readlane_b32 s2, v254, 12
	s_addc_u32 s3, s2, s83
	s_waitcnt lgkmcnt(1)
	v_max_f32_e32 v4, v4, v4
	s_waitcnt lgkmcnt(0)
	v_max_f32_e32 v3, v3, v3
	v_max_f32_e32 v2, v2, v3
	v_xor_b32_e32 v3, 4, v244
	v_cmp_lt_i32_e32 vcc, v3, v5
	v_max_f32_e32 v0, v0, v4
	s_nop 0
	v_cndmask_b32_e32 v3, v244, v3, vcc
	v_lshlrev_b32_e32 v3, 2, v3
	ds_bpermute_b32 v4, v3, v0
	ds_bpermute_b32 v3, v3, v2
	s_waitcnt lgkmcnt(1)
	v_max_f32_e32 v4, v4, v4
	s_waitcnt lgkmcnt(0)
	v_max_f32_e32 v3, v3, v3
	v_max_f32_e32 v2, v2, v3
	v_xor_b32_e32 v3, 8, v244
	v_cmp_lt_i32_e32 vcc, v3, v5
	v_max_f32_e32 v0, v0, v4
	s_nop 0
	v_cndmask_b32_e32 v3, v244, v3, vcc
	v_lshlrev_b32_e32 v3, 2, v3
	ds_bpermute_b32 v4, v3, v0
	ds_bpermute_b32 v3, v3, v2
	s_waitcnt lgkmcnt(1)
	v_max_f32_e32 v4, v4, v4
	s_waitcnt lgkmcnt(0)
	v_max_f32_e32 v3, v3, v3
	v_max_f32_e32 v2, v2, v3
	v_xor_b32_e32 v3, 16, v244
	v_cmp_lt_i32_e32 vcc, v3, v5
	v_max_f32_e32 v0, v0, v4
	s_nop 0
	v_cndmask_b32_e32 v3, v244, v3, vcc
	v_lshlrev_b32_e32 v3, 2, v3
	ds_bpermute_b32 v4, v3, v0
	ds_bpermute_b32 v3, v3, v2
	s_waitcnt lgkmcnt(1)
	v_max_f32_e32 v4, v4, v4
	s_waitcnt lgkmcnt(0)
	v_max_f32_e32 v3, v3, v3
	v_max_f32_e32 v2, v2, v3
	v_xor_b32_e32 v3, 32, v244
	v_cmp_lt_i32_e32 vcc, v3, v5
	v_max_f32_e32 v0, v0, v4
	s_nop 0
	v_cndmask_b32_e32 v3, v244, v3, vcc
	v_lshlrev_b32_e32 v3, 2, v3
	ds_bpermute_b32 v4, v3, v0
	ds_bpermute_b32 v3, v3, v2
	s_waitcnt lgkmcnt(1)
	v_max_f32_e32 v4, v4, v4
	v_max_f32_e32 v0, v0, v4
	s_waitcnt lgkmcnt(0)
	v_max_f32_e32 v3, v3, v3
	v_max_f32_e32 v2, v2, v3
	v_mul_f32_e32 v0, 0x41b8aa3b, v0
	v_fmaak_f32 v227, v2, v0, 0x42840000
	s_branch .LBB9_239
